# P0 rmsnorm loop: 7 loop-invariant gain-vector loads (reloaded and waited per row) loaded once before the loop
# speedup vs baseline: 1.0069x; 1.0069x over previous
.LBB0_87:
	s_cmp_lt_i32 s80, 0x8000
	s_cselect_b64 s[0:1], -1, 0
	v_writelane_b32 v255, s0, 33
	s_cmpk_gt_i32 s80, 0x7fff
	v_mbcnt_lo_u32_b32 v254, -1, 0
	v_writelane_b32 v255, s1, 34
	s_cbranch_scc1 .LBB0_90
	v_ashrrev_i32_e32 v11, 31, v10
	v_lshlrev_b64 v[6:7], 4, v[10:11]
	v_lshl_add_u64 v[12:13], s[62:63], 0, v[6:7]
	global_load_dwordx4 v[2:5], v[12:13], off
	v_mbcnt_hi_u32_b32 v8, -1, v254
	v_and_b32_e32 v9, 64, v8
	v_add_u32_e32 v9, 64, v9
	v_xor_b32_e32 v14, 1, v8
	v_cmp_lt_i32_e32 vcc, v14, v9
	s_mov_b64 s[0:1], 0x1000
	s_ashr_i32 s81, s80, 31
	v_cndmask_b32_e32 v14, v8, v14, vcc
	v_lshlrev_b32_e32 v26, 2, v14
	v_xor_b32_e32 v14, 2, v8
	v_cmp_lt_i32_e32 vcc, v14, v9
	s_mov_b64 s[6:7], 0x1c00
	v_lshl_add_u64 v[20:21], v[12:13], 0, s[6:7]
	v_cndmask_b32_e32 v14, v8, v14, vcc
	v_lshlrev_b32_e32 v27, 2, v14
	v_xor_b32_e32 v14, 4, v8
	v_cmp_lt_i32_e32 vcc, v14, v9
	s_mov_b32 s3, 0x800000
	s_nop 0
	v_cndmask_b32_e32 v14, v8, v14, vcc
	v_lshlrev_b32_e32 v28, 2, v14
	v_xor_b32_e32 v14, 8, v8
	v_cmp_lt_i32_e32 vcc, v14, v9
	s_nop 1
	v_cndmask_b32_e32 v14, v8, v14, vcc
	v_lshlrev_b32_e32 v29, 2, v14
	v_xor_b32_e32 v14, 16, v8
	v_cmp_lt_i32_e32 vcc, v14, v9
	s_nop 1
	v_cndmask_b32_e32 v14, v8, v14, vcc
	v_lshlrev_b32_e32 v30, 2, v14
	v_xor_b32_e32 v14, 32, v8
	v_cmp_lt_i32_e32 vcc, v14, v9
	s_nop 1
	v_cndmask_b32_e32 v8, v8, v14, vcc
	v_lshl_add_u64 v[14:15], v[12:13], 0, s[0:1]
	s_mov_b64 s[0:1], 0x1400
	v_lshl_add_u64 v[16:17], v[12:13], 0, s[0:1]
	s_mov_b64 s[0:1], 0x1800
	v_lshl_add_u64 v[18:19], v[12:13], 0, s[0:1]
	s_lshl_b64 s[0:1], s[80:81], 12
	s_add_u32 s0, s78, s0
	s_addc_u32 s1, s79, s1
	v_lshlrev_b32_e32 v31, 2, v8
	v_lshl_add_u64 v[8:9], v[10:11], 3, s[0:1]
	s_mov_b64 s[0:1], 0x9c00e00
	s_ashr_i32 s83, s82, 31
	v_lshl_add_u64 v[22:23], v[8:9], 0, s[0:1]
	s_lshl_b64 s[0:1], s[82:83], 12
	s_lshl_b64 s[8:9], s[80:81], 13
	s_add_u32 s8, s60, s8
	s_addc_u32 s9, s61, s9
	v_lshl_add_u64 v[6:7], s[8:9], 0, v[6:7]
	v_lshl_add_u64 v[24:25], v[6:7], 0, s[6:7]
	s_lshl_b64 s[6:7], s[82:83], 13
	v_mov_b32_e32 v11, 0x358637bd
	s_mov_b32 s8, s80
	global_load_dwordx4 v[96:99], v[12:13], off offset:1024
	global_load_dwordx4 v[100:103], v[12:13], off offset:2048
	global_load_dwordx4 v[104:107], v[12:13], off offset:3072
	global_load_dwordx4 v[108:111], v[14:15], off
	global_load_dwordx4 v[112:115], v[16:17], off
	global_load_dwordx4 v[116:119], v[18:19], off
	global_load_dwordx4 v[120:123], v[20:21], off
.LBB0_89:
	global_load_dwordx4 v[32:35], v[24:25], off offset:-3072 nt
	global_load_dwordx4 v[36:39], v[24:25], off offset:-2048 nt
	global_load_dwordx4 v[6:9], v[24:25], off nt
	global_load_dwordx4 v[40:43], v[24:25], off offset:-1024 nt
	v_add_co_u32_e32 v60, vcc, 0xfffff000, v24
	s_add_i32 s8, s8, s82
	s_nop 0
	v_addc_co_u32_e32 v61, vcc, -1, v25, vcc
	global_load_dwordx4 v[44:47], v[60:61], off offset:-3072 nt
	global_load_dwordx4 v[48:51], v[60:61], off offset:-2048 nt
	global_load_dwordx4 v[52:55], v[60:61], off offset:-1024 nt
	global_load_dwordx4 v[56:59], v[24:25], off offset:-4096 nt
	s_cmpk_gt_i32 s8, 0x7fff
	v_lshl_add_u64 v[24:25], v[24:25], 0, s[6:7]
	s_waitcnt vmcnt(7)
	v_mul_f32_e32 v83, v32, v32
	s_waitcnt vmcnt(6)
	v_pk_mul_f32 v[60:61], v[38:39], v[38:39]
	v_pk_mul_f32 v[62:63], v[36:37], v[36:37]
	s_waitcnt vmcnt(4)
	v_mul_f32_e32 v64, v41, v41
	v_mul_f32_e32 v66, v43, v43
	v_mul_f32_e32 v81, v8, v8
	v_mul_f32_e32 v89, v9, v9
	v_pk_mov_b32 v[68:69], v[62:63], v[60:61] op_sel:[1,0]
	v_mov_b32_e32 v63, v61
	v_pk_fma_f32 v[60:61], v[40:41], v[40:41], v[64:65] op_sel_hi:[1,1,0]
	v_pk_fma_f32 v[64:65], v[42:43], v[42:43], v[66:67] op_sel_hi:[1,1,0]
	s_waitcnt vmcnt(3)
	v_mov_b32_e32 v70, v45
	s_waitcnt vmcnt(2)
	v_mov_b32_e32 v71, v49
	v_mov_b32_e32 v74, v47
	v_mov_b32_e32 v75, v51
	v_mov_b32_e32 v66, v44
	v_mov_b32_e32 v67, v48
	v_mov_b32_e32 v72, v46
	v_mov_b32_e32 v73, v50
	s_waitcnt vmcnt(1)
	v_pk_mul_f32 v[76:77], v[54:55], v[54:55]
	v_pk_mul_f32 v[78:79], v[52:53], v[52:53]
	v_pk_add_f32 v[62:63], v[68:69], v[62:63]
	v_mov_b32_e32 v61, v81
	v_mov_b32_e32 v65, v89
	v_pk_mul_f32 v[68:69], v[70:71], v[70:71]
	v_pk_mul_f32 v[70:71], v[74:75], v[74:75]
	v_pk_mov_b32 v[74:75], v[78:79], v[76:77] op_sel:[1,0]
	v_mov_b32_e32 v79, v77
	v_pk_add_f32 v[60:61], v[60:61], v[64:65]
	v_pk_fma_f32 v[64:65], v[66:67], v[66:67], v[68:69]
	v_pk_fma_f32 v[66:67], v[72:73], v[72:73], v[70:71]
	s_waitcnt vmcnt(0)
	v_mul_f32_e32 v80, v57, v57
	v_mul_f32_e32 v82, v59, v59
	v_pk_add_f32 v[68:69], v[74:75], v[78:79]
	v_pk_add_f32 v[64:65], v[64:65], v[66:67]
	v_mul_f32_e32 v84, v33, v33
	v_mul_f32_e32 v85, v34, v34
	v_mul_f32_e32 v86, v35, v35
	v_pk_fma_f32 v[76:77], v[56:57], v[56:57], v[80:81] op_sel_hi:[1,1,0]
	v_pk_fma_f32 v[80:81], v[58:59], v[58:59], v[82:83] op_sel_hi:[1,1,0]
	v_pk_add_f32 v[66:67], v[68:69], v[68:69] op_sel:[0,1] op_sel_hi:[1,0]
	v_pk_add_f32 v[64:65], v[64:65], v[64:65] op_sel:[0,1] op_sel_hi:[1,0]
	v_mov_b32_e32 v77, v85
	v_mov_b32_e32 v81, v86
	v_mov_b32_e32 v67, v84
	v_mov_b32_e32 v65, v83
	v_pk_add_f32 v[68:69], v[76:77], v[80:81]
	v_pk_add_f32 v[64:65], v[64:65], v[66:67]
	v_mul_f32_e32 v87, v6, v6
	v_pk_add_f32 v[64:65], v[64:65], v[68:69]
	v_mul_f32_e32 v88, v7, v7
	v_pk_add_f32 v[62:63], v[62:63], v[62:63] op_sel:[0,1] op_sel_hi:[1,0]
	v_pk_add_f32 v[64:65], v[64:65], v[64:65] op_sel:[0,1] op_sel_hi:[1,0]
	v_mov_b32_e32 v63, v88
	v_mov_b32_e32 v65, v87
	v_pk_add_f32 v[62:63], v[64:65], v[62:63]
	s_nop 0
	v_pk_add_f32 v[60:61], v[62:63], v[60:61]
	s_nop 0
	v_add_f32_e32 v60, v60, v61
	ds_bpermute_b32 v61, v26, v60
	s_waitcnt lgkmcnt(0)
	v_add_f32_e32 v60, v60, v61
	ds_bpermute_b32 v61, v27, v60
	s_waitcnt lgkmcnt(0)
	v_add_f32_e32 v60, v60, v61
	ds_bpermute_b32 v61, v28, v60
	s_waitcnt lgkmcnt(0)
	v_add_f32_e32 v60, v60, v61
	ds_bpermute_b32 v61, v29, v60
	s_waitcnt lgkmcnt(0)
	v_add_f32_e32 v60, v60, v61
	ds_bpermute_b32 v61, v30, v60
	s_waitcnt lgkmcnt(0)
	v_add_f32_e32 v60, v60, v61
	ds_bpermute_b32 v61, v31, v60
	s_waitcnt lgkmcnt(0)
	v_add_f32_e32 v60, v60, v61
	v_fmamk_f32 v60, v60, 0x3a000000, v11
	v_mul_f32_e32 v61, 0x4b800000, v60
	v_cmp_gt_f32_e32 vcc, s3, v60
	s_nop 1
	v_cndmask_b32_e32 v60, v60, v61, vcc
	v_rsq_f32_e32 v60, v60
	s_nop 0
	v_mul_f32_e32 v61, 0x45800000, v60
	v_cndmask_b32_e32 v62, v60, v61, vcc
	v_mul_f32_e32 v44, v44, v62
	v_mul_f32_e32 v45, v45, v62
	v_mul_f32_e32 v46, v46, v62
	v_mul_f32_e32 v47, v47, v62
	v_mul_f32_e32 v44, v2, v44
	v_mul_f32_e32 v45, v3, v45
	v_mul_f32_e32 v46, v4, v46
	v_mul_f32_e32 v47, v5, v47
	v_cvt_pk_bf16_f32 v60, v44, v45
	v_cvt_pk_bf16_f32 v61, v46, v47
	v_mov_b64_e32 v[44:45], v[96:97]
	v_mov_b64_e32 v[46:47], v[98:99]
	v_mul_f32_e32 v48, v48, v62
	v_mul_f32_e32 v49, v49, v62
	v_mul_f32_e32 v50, v50, v62
	v_mul_f32_e32 v51, v51, v62
	global_store_dwordx2 v[22:23], v[60:61], off offset:-3584
	v_mul_f32_e32 v32, v32, v62
	v_mul_f32_e32 v33, v33, v62
	v_mul_f32_e32 v34, v34, v62
	v_mul_f32_e32 v35, v35, v62
	v_mul_f32_e32 v36, v36, v62
	v_mul_f32_e32 v37, v37, v62
	v_mul_f32_e32 v38, v38, v62
	v_mul_f32_e32 v39, v39, v62
	v_mul_f32_e32 v6, v6, v62
	v_mul_f32_e32 v7, v7, v62
	v_mul_f32_e32 v8, v8, v62
	v_mul_f32_e32 v9, v9, v62
	v_mul_f32_e32 v44, v44, v48
	v_mul_f32_e32 v45, v45, v49
	v_mul_f32_e32 v46, v46, v50
	v_mul_f32_e32 v47, v47, v51
	v_cvt_pk_bf16_f32 v48, v44, v45
	v_cvt_pk_bf16_f32 v49, v46, v47
	v_mov_b64_e32 v[44:45], v[100:101]
	v_mov_b64_e32 v[46:47], v[102:103]
	v_mul_f32_e32 v50, v52, v62
	v_mul_f32_e32 v51, v53, v62
	v_mul_f32_e32 v52, v54, v62
	v_mul_f32_e32 v53, v55, v62
	global_store_dwordx2 v[22:23], v[48:49], off offset:-3072
	v_mul_f32_e32 v44, v44, v50
	v_mul_f32_e32 v45, v45, v51
	v_mul_f32_e32 v46, v46, v52
	v_mul_f32_e32 v47, v47, v53
	v_cvt_pk_bf16_f32 v48, v44, v45
	v_cvt_pk_bf16_f32 v49, v46, v47
	v_mov_b64_e32 v[44:45], v[104:105]
	v_mov_b64_e32 v[46:47], v[106:107]
	v_mul_f32_e32 v50, v56, v62
	v_mul_f32_e32 v51, v57, v62
	v_mul_f32_e32 v52, v58, v62
	v_mul_f32_e32 v53, v59, v62
	global_store_dwordx2 v[22:23], v[48:49], off offset:-2560
	v_mul_f32_e32 v44, v50, v44
	v_mul_f32_e32 v45, v51, v45
	v_mul_f32_e32 v46, v52, v46
	v_mul_f32_e32 v47, v53, v47
	v_cvt_pk_bf16_f32 v48, v44, v45
	v_cvt_pk_bf16_f32 v49, v46, v47
	v_mov_b64_e32 v[44:45], v[108:109]
	v_mov_b64_e32 v[46:47], v[110:111]
	v_mul_f32_e32 v32, v32, v44
	v_mul_f32_e32 v33, v33, v45
	v_mul_f32_e32 v34, v34, v46
	v_mul_f32_e32 v35, v35, v47
	global_store_dwordx2 v[22:23], v[48:49], off offset:-2048
	v_cvt_pk_bf16_f32 v44, v32, v33
	v_cvt_pk_bf16_f32 v45, v34, v35
	v_mov_b64_e32 v[32:33], v[112:113]
	v_mov_b64_e32 v[34:35], v[114:115]
	v_mul_f32_e32 v32, v36, v32
	v_mul_f32_e32 v33, v37, v33
	v_mul_f32_e32 v34, v38, v34
	v_mul_f32_e32 v35, v39, v35
	global_store_dwordx2 v[22:23], v[44:45], off offset:-1536
	v_cvt_pk_bf16_f32 v36, v32, v33
	v_cvt_pk_bf16_f32 v37, v34, v35
	v_mov_b64_e32 v[32:33], v[116:117]
	v_mov_b64_e32 v[34:35], v[118:119]
	v_mul_f32_e32 v38, v40, v62
	v_mul_f32_e32 v39, v41, v62
	v_mul_f32_e32 v40, v42, v62
	v_mul_f32_e32 v41, v43, v62
	global_store_dwordx2 v[22:23], v[36:37], off offset:-1024
	v_mul_f32_e32 v32, v38, v32
	v_mul_f32_e32 v33, v39, v33
	v_mul_f32_e32 v34, v40, v34
	v_mul_f32_e32 v35, v41, v35
	v_cvt_pk_bf16_f32 v36, v32, v33
	v_cvt_pk_bf16_f32 v37, v34, v35
	v_mov_b64_e32 v[32:33], v[120:121]
	v_mov_b64_e32 v[34:35], v[122:123]
	v_mul_f32_e32 v6, v6, v32
	v_mul_f32_e32 v7, v7, v33
	global_store_dwordx2 v[22:23], v[36:37], off offset:-512
	v_mul_f32_e32 v8, v8, v34
	v_mul_f32_e32 v9, v9, v35
	v_cvt_pk_bf16_f32 v6, v6, v7
	v_cvt_pk_bf16_f32 v7, v8, v9
	global_store_dwordx2 v[22:23], v[6:7], off
	v_lshl_add_u64 v[22:23], v[22:23], 0, s[0:1]
	s_cbranch_scc0 .LBB0_89
